# v36 + W_down layer-1 conversion moved from the layer-0 up-proj window to the ML-in idle window
# speedup vs baseline: 1.0064x; 1.0062x over previous
.LBB0_160:
	s_cmp_eq_u32 s101, 1
	s_cbranch_scc1 .Lcv1_ret
	s_cmp_eq_u32 s101, 4
	s_cbranch_scc1 .Lcv_relay_ret3
	s_cmp_eq_u32 s101, 5
	s_cbranch_scc1 .Lcv_relay_ret3
	s_cmp_lg_u32 s101, 0
	s_cbranch_scc1 .Lcv_relay_ret
	s_mov_b64 s[76:77], s[88:89]
	v_and_b32_e32 v20, 63, v0
	s_cmpk_gt_i32 s2, 0x407f
	v_mbcnt_lo_u32_b32 v166, -1, 0
	s_mov_b32 s72, s86
	s_mov_b64 s[78:79], s[90:91]
	s_cbranch_scc1 .LBB0_165
	v_mbcnt_hi_u32_b32 v4, -1, v166
	v_and_b32_e32 v5, 64, v4
	v_add_u32_e32 v5, 64, v5
	v_xor_b32_e32 v6, 1, v4
	v_cmp_lt_i32_e32 vcc, v6, v5
	s_load_dwordx2 s[4:5], s[0:1], 0x48
	v_mov_b32_e32 v3, 0
	v_cndmask_b32_e32 v6, v4, v6, vcc
	v_lshlrev_b32_e32 v19, 2, v6
	v_xor_b32_e32 v6, 2, v4
	v_cmp_lt_i32_e32 vcc, v6, v5
	v_lshlrev_b32_e32 v2, 4, v20
	s_waitcnt lgkmcnt(0)
	v_lshl_add_u64 v[22:23], s[4:5], 0, v[2:3]
	v_cndmask_b32_e32 v6, v4, v6, vcc
	v_lshlrev_b32_e32 v32, 2, v6
	v_xor_b32_e32 v6, 4, v4
	v_cmp_lt_i32_e32 vcc, v6, v5
	s_mov_b64 s[4:5], 0x4200000
	v_lshl_add_u64 v[26:27], s[76:77], 0, v[2:3]
	v_cndmask_b32_e32 v6, v4, v6, vcc
	v_lshlrev_b32_e32 v33, 2, v6
	v_xor_b32_e32 v6, 8, v4
	v_cmp_lt_i32_e32 vcc, v6, v5
	v_lshlrev_b32_e32 v37, 4, v20
	v_mov_b32_e32 v38, 0x358637bd
	v_cndmask_b32_e32 v6, v4, v6, vcc
	v_lshlrev_b32_e32 v34, 2, v6
	v_xor_b32_e32 v6, 16, v4
	v_cmp_lt_i32_e32 vcc, v6, v5
	s_mov_b32 s3, 0xf800000
	v_mov_b32_e32 v39, 0x260
	v_cndmask_b32_e32 v6, v4, v6, vcc
	v_lshlrev_b32_e32 v35, 2, v6
	v_xor_b32_e32 v6, 32, v4
	v_cmp_lt_i32_e32 vcc, v6, v5
	v_mov_b32_e32 v5, v3
	s_nop 0
	v_cndmask_b32_e32 v4, v4, v6, vcc
	v_lshlrev_b32_e32 v36, 2, v4
	v_lshlrev_b32_e32 v4, 3, v20
	v_lshl_add_u64 v[4:5], s[78:79], 0, v[4:5]
	v_lshl_add_u64 v[24:25], v[4:5], 0, s[4:5]
	s_mov_b32 s4, s2
	s_branch .LBB0_163

.Lcv3_ret:
	s_cmp_eq_u32 s101, 5
	s_cbranch_scc1 .Lcv3_done
	v_readlane_b32 s2, v254, 19
	v_readlane_b32 s87, v255, 4
	s_sub_i32 s2, s2, 77
	s_lshl_b32 s2, s2, 3
	s_add_i32 s2, s2, s87
	s_addk_i32 s2, 0x3800
	s_movk_i32 s43, 0x598
	s_movk_i32 s100, 0x3fff
	s_mov_b32 s101, 5
	s_mov_b32 s7, 0
	s_branch .Lcv_relay_fwd

.LBB0_2040:
	s_waitcnt vmcnt(0)
	s_barrier
	v_readlane_b32 s100, v254, 43
	v_readlane_b32 s101, v254, 19
	s_cmp_lg_u32 s100, 0
	s_cbranch_scc1 .Lwd_entry
	s_cmpk_lt_u32 s101, 32
	s_cbranch_scc1 .Lcv2_skip
	v_writelane_b32 v200, s2, 0
	v_writelane_b32 v200, s3, 1
	v_writelane_b32 v200, s4, 2
	v_writelane_b32 v200, s5, 3
	v_writelane_b32 v200, s6, 4
	v_writelane_b32 v200, s7, 5
	v_writelane_b32 v200, s8, 6
	v_writelane_b32 v200, s9, 7
	v_writelane_b32 v200, s10, 8
	v_writelane_b32 v200, s11, 9
	v_writelane_b32 v200, s12, 10
	v_writelane_b32 v200, s13, 11
	v_writelane_b32 v200, s14, 12
	v_writelane_b32 v200, s15, 13
	v_writelane_b32 v200, s16, 14
	v_writelane_b32 v200, s17, 15
	v_writelane_b32 v200, s18, 16
	v_writelane_b32 v200, s19, 17
	v_writelane_b32 v200, s20, 18
	v_writelane_b32 v200, s21, 19
	v_writelane_b32 v200, s22, 20
	v_writelane_b32 v200, s23, 21
	v_writelane_b32 v200, s24, 22
	v_writelane_b32 v200, s25, 23
	v_writelane_b32 v200, s26, 24
	v_writelane_b32 v200, s27, 25
	v_writelane_b32 v200, s28, 26
	v_writelane_b32 v200, s29, 27
	v_writelane_b32 v200, s30, 28
	v_writelane_b32 v200, s31, 29
	v_writelane_b32 v200, s32, 30
	v_writelane_b32 v200, s33, 31
	v_writelane_b32 v200, s34, 32
	v_writelane_b32 v200, s35, 33
	v_writelane_b32 v200, s36, 34
	v_writelane_b32 v200, s37, 35
	v_writelane_b32 v200, s38, 36
	v_writelane_b32 v200, s39, 37
	v_writelane_b32 v200, s40, 38
	v_writelane_b32 v200, s41, 39
	v_writelane_b32 v200, s42, 40
	v_writelane_b32 v200, s43, 41
	v_writelane_b32 v200, s44, 42
	v_writelane_b32 v200, s45, 43
	v_writelane_b32 v200, s46, 44
	v_writelane_b32 v200, s47, 45
	v_writelane_b32 v200, s48, 46
	v_writelane_b32 v200, s49, 47
	v_writelane_b32 v200, s50, 48
	v_writelane_b32 v200, s51, 49
	v_writelane_b32 v200, s52, 50
	v_writelane_b32 v200, s53, 51
	v_writelane_b32 v200, s54, 52
	v_writelane_b32 v200, s55, 53
	v_writelane_b32 v200, s56, 54
	v_writelane_b32 v200, s57, 55
	v_writelane_b32 v200, s58, 56
	v_writelane_b32 v200, s59, 57
	v_writelane_b32 v200, s60, 58
	v_writelane_b32 v200, s61, 59
	v_writelane_b32 v200, s62, 60
	v_writelane_b32 v200, s63, 61
	v_writelane_b32 v200, s64, 62
	v_writelane_b32 v200, s65, 63
	v_writelane_b32 v201, s66, 0
	v_writelane_b32 v201, s67, 1
	v_writelane_b32 v201, s68, 2
	v_writelane_b32 v201, s69, 3
	v_writelane_b32 v201, s70, 4
	v_writelane_b32 v201, s71, 5
	v_writelane_b32 v201, s72, 6
	v_writelane_b32 v201, s73, 7
	v_writelane_b32 v201, s74, 8
	v_writelane_b32 v201, s75, 9
	v_writelane_b32 v201, s76, 10
	v_writelane_b32 v201, s77, 11
	v_writelane_b32 v201, s78, 12
	v_writelane_b32 v201, s79, 13
	v_writelane_b32 v201, s80, 14
	v_writelane_b32 v201, s81, 15
	v_writelane_b32 v201, s82, 16
	v_writelane_b32 v201, s83, 17
	v_writelane_b32 v201, s84, 18
	v_writelane_b32 v201, s85, 19
	v_writelane_b32 v201, s86, 20
	v_writelane_b32 v201, s87, 21
	v_writelane_b32 v201, s88, 22
	v_writelane_b32 v201, s89, 23
	v_writelane_b32 v201, s90, 24
	v_writelane_b32 v201, s91, 25
	v_writelane_b32 v201, s92, 26
	v_writelane_b32 v201, s93, 27
	v_writelane_b32 v201, s94, 28
	v_writelane_b32 v201, s95, 29
	v_writelane_b32 v201, s96, 30
	v_writelane_b32 v201, s97, 31
	v_writelane_b32 v201, s98, 32
	v_writelane_b32 v201, s99, 33
	s_load_dwordx4 s[88:91], s[0:1], 0xb8
	v_mbcnt_lo_u32_b32 v0, -1, 0
	v_mbcnt_hi_u32_b32 v0, -1, v0
	v_readlane_b32 s87, v255, 4
	s_waitcnt lgkmcnt(0)
	v_and_b32_e32 v21, 31, v0
	v_bfe_u32 v31, v0, 5, 1
	v_lshlrev_b32_e32 v2, 2, v21
	v_mul_u32_u24_e32 v3, 0x84, v31
	v_bfe_u32 v29, v0, 3, 3
	s_lshl_b32 s2, s87, 14
	s_add_i32 s3, s2, 0
	v_add3_u32 v28, s3, v2, v3
	v_lshlrev_b32_e32 v2, 3, v0
	v_and_b32_e32 v2, 56, v2
	v_mul_u32_u24_e32 v4, 0x84, v2
	v_lshlrev_b32_e32 v5, 2, v29
	s_mov_b32 s7, 0
	v_mov_b32_e32 v3, 0
	v_add3_u32 v30, s3, v4, v5
	v_lshlrev_b32_e32 v18, 1, v2
	s_sub_i32 s2, s101, 32
	s_lshl_b32 s2, s2, 3
	s_add_i32 s2, s2, s87
	s_addk_i32 s2, 0x3000
	s_movk_i32 s43, 0x700
	s_movk_i32 s100, 0x37ff
	s_mov_b32 s101, 2
	s_branch .Lcv_relay_fwd
